# v070 + attention work-queue claim atomic issued mid-item (before softmax exps) and consumed at item end behind a counted vmcnt, hiding the returning-atomic latency per item
# speedup vs baseline: 1.0041x; 1.0041x over previous
; __device__ __forceinline__ void attn_v2(const KA& A, const Ctx& F, int l) {
;     ...
;         int item;
;         if (first_) { item = F.bid; first_ = false; }
;         else { if (F.tid == 0) *slot = 256u + __hip_atomic_fetch_add(ctr, 1u, __ATOMIC_RELAXED, __HIP_MEMORY_SCOPE_AGENT);
;                __syncthreads();
;                item = (int)*slot; }
.LBB0_198:
	s_or_b64 exec, exec, s[12:13]
	s_nop 0
	v_readfirstlane_b32 s12, v1
	s_nop 1
	v_add_u32_e32 v0, s12, v0
	v_readlane_b32 s12, v253, 50
	v_add_u32_e32 v0, 0x100, v0
	s_nop 0
	v_mov_b32_e32 v1, s12
	ds_write_b32 v1, v0

; __device__ __forceinline__ float xmax32(float v) { auto r = __builtin_amdgcn_permlane32_swap(__float_as_uint(v), __float_as_uint(v), false, false); return fmaxf(__uint_as_float(r[0]), __uint_as_float(r[1])); }
; __device__ __forceinline__ int crow16(int g, int hh) { return (g & 3) + 8 * (g >> 2) + 4 * hh; }
; __device__ __forceinline__ void attn_v2(const KA& A, const Ctx& F, int l) {
;     ...
;         const int kbase = i0 + 32 * w - 128;
;         float mx = -3.0e38f;
; #pragma unroll
;         for (int kt = 0; kt < 5; ++kt) {
;             if (kt == 0 || kt == 4 || kbase < 0) {
; #pragma unroll
;                 for (int gq = 0; gq < 16; ++gq) { const int kl = crow16(gq, hh); const int dist = q + 128 - 32 * kt - kl;
;                     const bool ok = (dist >= 0) && (dist <= 128) && (kbase + 32 * kt + kl >= 0);
;                     if (!ok) p[kt][gq] = -3.0e38f; } }
; #pragma unroll
;             for (int gq = 0; gq < 16; ++gq) mx = fmaxf(mx, p[kt][gq]);
;         }
;         mx = xmax32(mx);
;         const float sc = 0.125f * 1.4426950408889634f;
;         float l = 0.f;
; #pragma unroll
;         for (int kt = 0; kt < 5; ++kt)
; #pragma unroll
;             for (int gq = 0; gq < 16; ++gq) { const float e = __builtin_amdgcn_exp2f((p[kt][gq] - mx) * sc); p[kt][gq] = e; l += e; }
.LBB0_206:
	s_sub_i32 s10, 0x7f, s19
	v_cmp_lt_i32_e32 vcc, s10, v143
	s_and_b64 vcc, s[40:41], vcc
	s_waitcnt lgkmcnt(0)
	s_barrier
	v_cndmask_b32_e32 v80, v237, v48, vcc
	v_cmp_le_i32_e32 vcc, s10, v143
	s_and_b64 vcc, s[42:43], vcc
	s_nop 0
	v_cndmask_b32_e32 v82, v237, v49, vcc
	v_cmp_lt_i32_e32 vcc, s10, v144
	s_and_b64 vcc, s[44:45], vcc
	s_nop 0
	v_cndmask_b32_e32 v83, v237, v50, vcc
	v_cmp_lt_i32_e32 vcc, s10, v145
	s_and_b64 vcc, s[46:47], vcc
	s_nop 0
	v_cndmask_b32_e32 v51, v237, v51, vcc
	v_cmp_lt_i32_e32 vcc, s10, v146
	s_and_b64 vcc, s[48:49], vcc
	s_nop 0
	v_cndmask_b32_e32 v84, v237, v52, vcc
	v_cmp_lt_i32_e32 vcc, s10, v147
	s_and_b64 vcc, s[50:51], vcc
	s_nop 0
	v_cndmask_b32_e32 v53, v237, v53, vcc
	v_cmp_lt_i32_e32 vcc, s10, v148
	s_and_b64 vcc, s[52:53], vcc
	s_nop 0
	v_cndmask_b32_e32 v54, v237, v54, vcc
	v_cmp_lt_i32_e32 vcc, s10, v149
	s_and_b64 vcc, s[54:55], vcc
	s_nop 0
	v_cndmask_b32_e32 v55, v237, v55, vcc
	v_cmp_lt_i32_e32 vcc, s10, v150
	s_and_b64 vcc, s[56:57], vcc
	s_nop 0
	v_cndmask_b32_e32 v56, v237, v56, vcc
	v_cmp_lt_i32_e32 vcc, s10, v151
	s_and_b64 vcc, s[58:59], vcc
	s_nop 0
	v_cndmask_b32_e32 v57, v237, v57, vcc
	v_cmp_lt_i32_e32 vcc, s10, v152
	s_and_b64 vcc, s[60:61], vcc
	s_nop 0
	v_cndmask_b32_e32 v58, v237, v58, vcc
	v_cmp_lt_i32_e32 vcc, s10, v153
	s_and_b64 vcc, s[62:63], vcc
	s_nop 0
	v_cndmask_b32_e32 v59, v237, v59, vcc
	v_cmp_lt_i32_e32 vcc, s10, v154
	s_and_b64 vcc, s[64:65], vcc
	s_nop 0
	v_cndmask_b32_e32 v60, v237, v60, vcc
	v_cmp_lt_i32_e32 vcc, s10, v155
	s_and_b64 vcc, s[66:67], vcc
	s_nop 0
	v_cndmask_b32_e32 v61, v237, v61, vcc
	v_cmp_lt_i32_e32 vcc, s10, v156
	s_and_b64 vcc, s[68:69], vcc
	s_nop 0
	v_cndmask_b32_e32 v62, v237, v62, vcc
	v_cmp_lt_i32_e32 vcc, s10, v157
	s_mov_b32 s10, 0xff61b1e6
	v_max3_f32 v48, v80, s10, v82
	v_max3_f32 v48, v48, v83, v51
	v_max3_f32 v48, v48, v84, v53
	v_max3_f32 v48, v48, v54, v55
	v_max3_f32 v48, v48, v56, v57
	s_and_b64 vcc, s[70:71], vcc
	v_max3_f32 v48, v48, v58, v59
	s_not_b32 s10, s19
	v_cndmask_b32_e32 v63, v237, v63, vcc
	v_max3_f32 v48, v48, v60, v61
	v_cmp_lt_i32_e32 vcc, s10, v143
	v_max3_f32 v48, v48, v62, v63
	s_and_b64 vcc, s[72:73], vcc
	v_max3_f32 v48, v48, v32, v33
	v_cndmask_b32_e32 v128, v237, v64, vcc
	v_cmp_le_i32_e32 vcc, s10, v143
	v_max3_f32 v48, v48, v34, v35
	s_and_b64 vcc, s[74:75], vcc
	v_max3_f32 v48, v48, v36, v37
	v_cndmask_b32_e32 v127, v237, v65, vcc
	v_cmp_lt_i32_e32 vcc, s10, v144
	v_max3_f32 v48, v48, v38, v39
	s_and_b64 vcc, s[76:77], vcc
	v_max3_f32 v48, v48, v40, v41
	v_cndmask_b32_e32 v126, v237, v66, vcc
	v_cmp_lt_i32_e32 vcc, s10, v145
	v_max3_f32 v48, v48, v42, v43
	s_and_b64 vcc, s[78:79], vcc
	v_max3_f32 v48, v48, v44, v45
	v_cndmask_b32_e32 v125, v237, v67, vcc
	v_cmp_gt_i32_e32 vcc, s19, v158
	v_max3_f32 v48, v48, v46, v47
	s_and_b64 vcc, s[80:81], vcc
	v_max3_f32 v48, v48, v16, v17
	v_cndmask_b32_e32 v124, v237, v68, vcc
	v_cmp_gt_i32_e32 vcc, s19, v159
	v_max3_f32 v48, v48, v18, v19
	s_and_b64 vcc, s[26:27], vcc
	v_max3_f32 v48, v48, v20, v21
	v_cndmask_b32_e32 v49, v237, v69, vcc
	v_cmp_gt_i32_e32 vcc, s19, v160
	v_max3_f32 v48, v48, v22, v23
	s_and_b64 vcc, s[84:85], vcc
	v_max3_f32 v48, v48, v24, v25
	v_cndmask_b32_e32 v50, v237, v70, vcc
	v_cmp_gt_i32_e32 vcc, s19, v161
	v_max3_f32 v48, v48, v26, v27
	s_and_b64 vcc, s[86:87], vcc
	v_max3_f32 v48, v48, v28, v29
	v_cndmask_b32_e32 v52, v237, v71, vcc
	v_cmp_gt_i32_e32 vcc, s19, v162
	v_max3_f32 v48, v48, v30, v31
	s_and_b64 vcc, s[88:89], vcc
	v_max3_f32 v48, v48, v0, v1
	v_cndmask_b32_e32 v123, v237, v72, vcc
	v_cmp_gt_i32_e32 vcc, s19, v163
	v_max3_f32 v48, v48, v2, v3
	s_and_b64 vcc, s[90:91], vcc
	v_max3_f32 v48, v48, v4, v5
	v_cndmask_b32_e32 v122, v237, v73, vcc
	v_cmp_gt_i32_e32 vcc, s19, v164
	v_max3_f32 v48, v48, v6, v7
	s_and_b64 vcc, s[92:93], vcc
	v_max3_f32 v48, v48, v8, v9
	v_cndmask_b32_e32 v121, v237, v74, vcc
	v_cmp_gt_i32_e32 vcc, s19, v165
	v_max3_f32 v48, v48, v10, v11
	s_and_b64 vcc, s[94:95], vcc
	v_max3_f32 v48, v48, v12, v13
	v_cndmask_b32_e32 v120, v237, v75, vcc
	v_cmp_gt_i32_e32 vcc, s19, v166
	v_max3_f32 v48, v48, v14, v15
	s_and_b64 vcc, s[96:97], vcc
	v_cndmask_b32_e32 v119, v237, v76, vcc
	v_cmp_gt_i32_e32 vcc, s19, v167
	v_max3_f32 v48, v48, v128, v127
	s_and_b64 vcc, s[2:3], vcc
	v_max3_f32 v48, v48, v126, v125
	v_cndmask_b32_e32 v118, v237, v77, vcc
	v_cmp_gt_i32_e32 vcc, s19, v168
	v_max3_f32 v48, v48, v124, v49
	s_and_b64 vcc, s[4:5], vcc
	v_max3_f32 v48, v48, v50, v52
	v_cndmask_b32_e32 v117, v237, v78, vcc
	v_cmp_gt_i32_e32 vcc, s19, v169
	v_max3_f32 v48, v48, v123, v122
	s_and_b64 vcc, s[6:7], vcc
	v_max3_f32 v48, v48, v121, v120
	v_cndmask_b32_e32 v116, v237, v79, vcc
	v_max3_f32 v48, v48, v119, v118
	v_max3_f32 v48, v48, v117, v116
	v_mov_b32_e32 v64, v48
	s_nop 1
	v_permlane32_swap_b32_e32 v48, v64
	v_max_f32_e32 v64, v64, v64
	v_max_f32_e32 v48, v48, v48
	v_max_f32_e32 v48, v48, v64
	v_sub_f32_e32 v64, v80, v48
	v_sub_f32_e32 v65, v82, v48
	v_sub_f32_e32 v53, v53, v48
	v_mul_f32_e32 v64, 0x3e38aa3b, v64
	v_mul_f32_e32 v65, 0x3e38aa3b, v65
	v_mul_f32_e32 v53, 0x3e38aa3b, v53
	v_exp_f32_e32 v90, v64
	v_exp_f32_e32 v92, v65
	v_sub_f32_e32 v65, v83, v48
	v_exp_f32_e32 v108, v53
	v_sub_f32_e32 v53, v54, v48
	v_mul_f32_e32 v65, 0x3e38aa3b, v65
	v_sub_f32_e32 v51, v51, v48
	v_mul_f32_e32 v53, 0x3e38aa3b, v53
	v_exp_f32_e32 v95, v65
	v_mul_f32_e32 v51, 0x3e38aa3b, v51
	v_exp_f32_e32 v110, v53
	v_sub_f32_e32 v53, v55, v48
	v_exp_f32_e32 v98, v51
	v_mul_f32_e32 v53, 0x3e38aa3b, v53
	v_add_f32_e32 v64, 0, v90
	v_exp_f32_e32 v112, v53
	v_sub_f32_e32 v53, v56, v48
	v_add_f32_e32 v64, v92, v64
; __device__ __forceinline__ float xsum32(float v) { auto r = __builtin_amdgcn_permlane32_swap(__float_as_uint(v), __float_as_uint(v), false, false); return __uint_as_float(r[0]) + __uint_as_float(r[1]); }
; __device__ __forceinline__ void attn_v2(const KA& A, const Ctx& F, int l) {
;     ...
;         else { if (F.tid == 0) *slot = 256u + __hip_atomic_fetch_add(ctr, 1u, __ATOMIC_RELAXED, __HIP_MEMORY_SCOPE_AGENT);
;     ...
;         float l = 0.f;
; #pragma unroll
;         for (int kt = 0; kt < 5; ++kt)
; #pragma unroll
;             for (int gq = 0; gq < 16; ++gq) { const float e = __builtin_amdgcn_exp2f((p[kt][gq] - mx) * sc); p[kt][gq] = e; l += e; }
;         l = xsum32(l);
	v_mul_f32_e32 v53, 0x3e38aa3b, v53
	v_add_f32_e32 v64, v95, v64
	v_exp_f32_e32 v91, v53
	v_sub_f32_e32 v53, v57, v48
	v_sub_f32_e32 v33, v33, v48
	v_add_f32_e32 v51, v98, v64
	v_sub_f32_e32 v64, v84, v48
	v_mul_f32_e32 v53, 0x3e38aa3b, v53
	v_mul_f32_e32 v33, 0x3e38aa3b, v33
	v_mul_f32_e32 v64, 0x3e38aa3b, v64
	v_exp_f32_e32 v99, v53
	v_sub_f32_e32 v53, v58, v48
	v_exp_f32_e32 v87, v33
	v_sub_f32_e32 v33, v34, v48
	v_exp_f32_e32 v102, v64
	v_mul_f32_e32 v53, 0x3e38aa3b, v53
	v_mul_f32_e32 v33, 0x3e38aa3b, v33
	v_exp_f32_e32 v103, v53
	v_sub_f32_e32 v53, v59, v48
	v_exp_f32_e32 v93, v33
	v_sub_f32_e32 v33, v35, v48
	v_mul_f32_e32 v53, 0x3e38aa3b, v53
	v_mul_f32_e32 v33, 0x3e38aa3b, v33
	v_exp_f32_e32 v105, v53
	v_sub_f32_e32 v53, v60, v48
	v_exp_f32_e32 v96, v33
	v_sub_f32_e32 v33, v36, v48
	v_add_f32_e32 v51, v102, v51
	v_mul_f32_e32 v53, 0x3e38aa3b, v53
	v_mul_f32_e32 v33, 0x3e38aa3b, v33
	v_add_f32_e32 v51, v108, v51
	v_exp_f32_e32 v107, v53
	v_sub_f32_e32 v53, v61, v48
	v_exp_f32_e32 v100, v33
	v_sub_f32_e32 v33, v37, v48
	v_add_f32_e32 v51, v110, v51
	v_mul_f32_e32 v53, 0x3e38aa3b, v53
	v_mul_f32_e32 v33, 0x3e38aa3b, v33
	v_add_f32_e32 v51, v112, v51
	v_exp_f32_e32 v113, v53
	v_sub_f32_e32 v53, v62, v48
	v_exp_f32_e32 v106, v33
	v_sub_f32_e32 v33, v38, v48
	v_add_f32_e32 v51, v91, v51
	v_mul_f32_e32 v53, 0x3e38aa3b, v53
	v_mul_f32_e32 v33, 0x3e38aa3b, v33
	v_add_f32_e32 v51, v99, v51
	v_exp_f32_e32 v114, v53
	v_sub_f32_e32 v53, v63, v48
	v_exp_f32_e32 v109, v33
	v_sub_f32_e32 v33, v39, v48
	v_add_f32_e32 v51, v103, v51
	v_mul_f32_e32 v53, 0x3e38aa3b, v53
	v_sub_f32_e32 v32, v32, v48
	v_mul_f32_e32 v33, 0x3e38aa3b, v33
	v_add_f32_e32 v51, v105, v51
	v_exp_f32_e32 v115, v53
	v_mul_f32_e32 v32, 0x3e38aa3b, v32
	v_exp_f32_e32 v111, v33
	v_sub_f32_e32 v33, v40, v48
	v_add_f32_e32 v51, v107, v51
	v_exp_f32_e32 v82, v32
	v_mul_f32_e32 v33, 0x3e38aa3b, v33
	v_add_f32_e32 v51, v113, v51
	v_exp_f32_e32 v73, v33
	s_mov_b64 exec, s[8:9]
	s_cbranch_execz .Latt_pf_skip
	v_mov_b32_e32 v178, 1
	s_nop 0
	global_atomic_add v178, v81, v178, s[16:17] sc0
.Latt_pf_skip:
	s_mov_b64 exec, -1
	v_sub_f32_e32 v33, v41, v48
	v_sub_f32_e32 v17, v17, v48
	v_sub_f32_e32 v1, v1, v48
	v_add_f32_e32 v51, v114, v51
	v_mul_f32_e32 v33, 0x3e38aa3b, v33
	v_mul_f32_e32 v17, 0x3e38aa3b, v17
	v_mul_f32_e32 v1, 0x3e38aa3b, v1
	v_add_f32_e32 v51, v115, v51
	v_exp_f32_e32 v78, v33
	v_sub_f32_e32 v33, v42, v48
	v_exp_f32_e32 v70, v17
	v_sub_f32_e32 v17, v18, v48
	v_exp_f32_e32 v56, v1
	v_sub_f32_e32 v1, v2, v48
	v_add_f32_e32 v32, v82, v51
	v_mul_f32_e32 v33, 0x3e38aa3b, v33
	v_mul_f32_e32 v17, 0x3e38aa3b, v17
	v_mul_f32_e32 v1, 0x3e38aa3b, v1
	v_add_f32_e32 v32, v87, v32
	v_exp_f32_e32 v83, v33
	v_sub_f32_e32 v33, v43, v48
	v_exp_f32_e32 v74, v17
	v_sub_f32_e32 v17, v19, v48
	v_exp_f32_e32 v59, v1
	v_sub_f32_e32 v1, v3, v48
	v_add_f32_e32 v32, v93, v32
	v_mul_f32_e32 v33, 0x3e38aa3b, v33
	v_mul_f32_e32 v17, 0x3e38aa3b, v17
	v_mul_f32_e32 v1, 0x3e38aa3b, v1
	v_add_f32_e32 v32, v96, v32
	v_exp_f32_e32 v85, v33
	v_sub_f32_e32 v33, v44, v48
	v_exp_f32_e32 v76, v17
	v_sub_f32_e32 v17, v20, v48
	v_exp_f32_e32 v60, v1
	v_sub_f32_e32 v1, v4, v48
	v_add_f32_e32 v32, v100, v32
	v_mul_f32_e32 v33, 0x3e38aa3b, v33
	v_mul_f32_e32 v17, 0x3e38aa3b, v17
	v_mul_f32_e32 v1, 0x3e38aa3b, v1
	v_add_f32_e32 v32, v106, v32
	v_exp_f32_e32 v88, v33
	v_sub_f32_e32 v33, v45, v48
	v_exp_f32_e32 v79, v17
	v_sub_f32_e32 v17, v21, v48
	v_exp_f32_e32 v63, v1
	v_sub_f32_e32 v1, v5, v48
	v_add_f32_e32 v32, v109, v32
	v_mul_f32_e32 v33, 0x3e38aa3b, v33
	v_mul_f32_e32 v17, 0x3e38aa3b, v17
	v_mul_f32_e32 v1, 0x3e38aa3b, v1
	v_add_f32_e32 v32, v111, v32
	v_exp_f32_e32 v97, v33
	v_sub_f32_e32 v33, v46, v48
	v_exp_f32_e32 v86, v17
	v_sub_f32_e32 v17, v22, v48
	v_exp_f32_e32 v69, v1
	v_sub_f32_e32 v1, v6, v48
	v_add_f32_e32 v32, v73, v32
	v_mul_f32_e32 v33, 0x3e38aa3b, v33
	v_mul_f32_e32 v17, 0x3e38aa3b, v17
	v_mul_f32_e32 v1, 0x3e38aa3b, v1
	v_add_f32_e32 v32, v78, v32
	v_exp_f32_e32 v101, v33
	v_sub_f32_e32 v33, v47, v48
	v_exp_f32_e32 v89, v17
	v_sub_f32_e32 v17, v23, v48
	v_exp_f32_e32 v72, v1
	v_sub_f32_e32 v1, v7, v48
	v_add_f32_e32 v32, v83, v32
	v_mul_f32_e32 v33, 0x3e38aa3b, v33
	v_sub_f32_e32 v16, v16, v48
	v_mul_f32_e32 v17, 0x3e38aa3b, v17
	v_mul_f32_e32 v1, 0x3e38aa3b, v1
	v_add_f32_e32 v32, v85, v32
	v_exp_f32_e32 v104, v33
	v_mul_f32_e32 v16, 0x3e38aa3b, v16
	v_exp_f32_e32 v94, v17
	v_sub_f32_e32 v17, v24, v48
	v_exp_f32_e32 v75, v1
	v_sub_f32_e32 v1, v8, v48
	v_add_f32_e32 v32, v88, v32
	v_exp_f32_e32 v65, v16
	v_mul_f32_e32 v17, 0x3e38aa3b, v17
	v_mul_f32_e32 v1, 0x3e38aa3b, v1
	v_add_f32_e32 v32, v97, v32
	v_exp_f32_e32 v58, v17
	v_sub_f32_e32 v17, v25, v48
	v_exp_f32_e32 v44, v1
	v_sub_f32_e32 v1, v9, v48
	v_add_f32_e32 v32, v101, v32
	v_mul_f32_e32 v17, 0x3e38aa3b, v17
	v_mul_f32_e32 v1, 0x3e38aa3b, v1
	v_add_f32_e32 v32, v104, v32
	v_exp_f32_e32 v62, v17
	v_sub_f32_e32 v17, v26, v48
	v_exp_f32_e32 v51, v1
	v_sub_f32_e32 v1, v10, v48
	v_add_f32_e32 v16, v65, v32
	v_mul_f32_e32 v17, 0x3e38aa3b, v17
	v_mul_f32_e32 v1, 0x3e38aa3b, v1
	v_add_f32_e32 v16, v70, v16
	v_exp_f32_e32 v66, v17
	v_sub_f32_e32 v17, v27, v48
	v_exp_f32_e32 v54, v1
	v_sub_f32_e32 v1, v11, v48
	v_add_f32_e32 v16, v74, v16
	v_mul_f32_e32 v17, 0x3e38aa3b, v17
	v_mul_f32_e32 v1, 0x3e38aa3b, v1
	v_add_f32_e32 v16, v76, v16
	v_exp_f32_e32 v68, v17
	v_sub_f32_e32 v17, v28, v48
	v_exp_f32_e32 v55, v1
	v_sub_f32_e32 v1, v12, v48
	v_add_f32_e32 v16, v79, v16
	v_mul_f32_e32 v17, 0x3e38aa3b, v17
	v_mul_f32_e32 v1, 0x3e38aa3b, v1
	v_add_f32_e32 v16, v86, v16
	v_exp_f32_e32 v71, v17
	v_sub_f32_e32 v17, v29, v48
	v_exp_f32_e32 v57, v1
; __device__ __forceinline__ unsigned cvtpk(float lo, float hi) { f32x2_t v = {lo, hi}; bf16x2_t b = __builtin_convertvector(v, bf16x2_t); return __builtin_bit_cast(unsigned, b); }
; __device__ __forceinline__ float xsum32(float v) { auto r = __builtin_amdgcn_permlane32_swap(__float_as_uint(v), __float_as_uint(v), false, false); return __uint_as_float(r[0]) + __uint_as_float(r[1]); }
; __device__ __forceinline__ v4i16_t ds_tr16(const unsigned char* p) { return __builtin_amdgcn_ds_read_tr16_b64_v4i16((LAS v4i16_t*)p); }
; __device__ __forceinline__ void attn_v2(const KA& A, const Ctx& F, int l) {
;     ...
;         for (int kt = 0; kt < 5; ++kt)
; #pragma unroll
;             for (int gq = 0; gq < 16; ++gq) { const float e = __builtin_amdgcn_exp2f((p[kt][gq] - mx) * sc); p[kt][gq] = e; l += e; }
;         l = xsum32(l);
;         asm volatile("s_waitcnt lgkmcnt(0)" ::: "memory"); __builtin_amdgcn_s_barrier(); asm volatile("" ::: "memory");
;         f32x16 o[2]; o[0] = f32x16{}; o[1] = f32x16{};
;         const unsigned char* vb = VI + ((32 * w + 4 * hh + ((lane & 15) >> 2)) * ATT_VS + 16 * ((lane >> 4) & 1) + 4 * (lane & 3)) * 2;
; #pragma unroll
;         for (int kt = 0; kt < 5; ++kt)
; #pragma unroll
;             for (int s = 0; s < 2; ++s) {
;                 v4u pw; pw.x = cvtpk(p[kt][8 * s + 0], p[kt][8 * s + 1]); pw.y = cvtpk(p[kt][8 * s + 2], p[kt][8 * s + 3]); pw.z = cvtpk(p[kt][8 * s + 4], p[kt][8 * s + 5]); pw.w = cvtpk(p[kt][8 * s + 6], p[kt][8 * s + 7]);
;                 const bf16x8_t pb = __builtin_bit_cast(bf16x8_t, pw);
; #pragma unroll
;                 for (int dt = 0; dt < 2; ++dt) {
;                     const unsigned char* vp = vb + ((32 * kt + 16 * s) * ATT_VS + 32 * dt) * 2;
;                     const v4i16_t lo = ds_tr16(vp), hi = ds_tr16(vp + 8 * ATT_VS * 2);
;                     const bf16x8_t va = (bf16x8_t){lo[0], lo[1], lo[2], lo[3], hi[0], hi[1], hi[2], hi[3]};
;                     o[dt] = __builtin_amdgcn_mfma_f32_32x32x16_bf16(va, pb, o[dt], 0, 0, 0);
;                 }
;             }
	v_sub_f32_e32 v1, v13, v48
	v_add_f32_e32 v16, v89, v16
	v_mul_f32_e32 v17, 0x3e38aa3b, v17
	v_mul_f32_e32 v1, 0x3e38aa3b, v1
	v_add_f32_e32 v16, v94, v16
	v_exp_f32_e32 v77, v17
	v_sub_f32_e32 v17, v30, v48
	v_exp_f32_e32 v61, v1
	v_sub_f32_e32 v1, v14, v48
	v_add_f32_e32 v16, v58, v16
	v_mul_f32_e32 v17, 0x3e38aa3b, v17
	v_mul_f32_e32 v1, 0x3e38aa3b, v1
	v_add_f32_e32 v16, v62, v16
	v_exp_f32_e32 v80, v17
	v_sub_f32_e32 v17, v31, v48
	v_exp_f32_e32 v64, v1
	v_sub_f32_e32 v1, v15, v48
	v_add_f32_e32 v16, v66, v16
	v_mul_f32_e32 v17, 0x3e38aa3b, v17
	v_sub_f32_e32 v0, v0, v48
	v_mul_f32_e32 v1, 0x3e38aa3b, v1
	v_add_f32_e32 v16, v68, v16
	v_exp_f32_e32 v84, v17
	v_mul_f32_e32 v0, 0x3e38aa3b, v0
	v_exp_f32_e32 v67, v1
	v_sub_f32_e32 v1, v128, v48
	v_add_f32_e32 v16, v71, v16
	v_exp_f32_e32 v53, v0
	v_mul_f32_e32 v1, 0x3e38aa3b, v1
	v_add_f32_e32 v16, v77, v16
	v_exp_f32_e32 v42, v1
	v_sub_f32_e32 v1, v127, v48
	v_add_f32_e32 v16, v80, v16
	v_mul_f32_e32 v1, 0x3e38aa3b, v1
	v_add_f32_e32 v16, v84, v16
	v_exp_f32_e32 v43, v1
	v_sub_f32_e32 v1, v126, v48
	v_add_f32_e32 v0, v53, v16
	v_mul_f32_e32 v1, 0x3e38aa3b, v1
	v_add_f32_e32 v0, v56, v0
	v_exp_f32_e32 v45, v1
	v_sub_f32_e32 v1, v125, v48
	v_add_f32_e32 v0, v59, v0
	v_mul_f32_e32 v1, 0x3e38aa3b, v1
	v_add_f32_e32 v0, v60, v0
	v_exp_f32_e32 v46, v1
	v_sub_f32_e32 v1, v124, v48
	v_add_f32_e32 v0, v63, v0
	v_mul_f32_e32 v1, 0x3e38aa3b, v1
	v_add_f32_e32 v0, v69, v0
	v_exp_f32_e32 v47, v1
	v_sub_f32_e32 v1, v49, v48
	v_add_f32_e32 v0, v72, v0
	v_mul_f32_e32 v1, 0x3e38aa3b, v1
	v_add_f32_e32 v0, v75, v0
	v_exp_f32_e32 v49, v1
	v_sub_f32_e32 v1, v50, v48
	v_add_f32_e32 v0, v44, v0
	v_mul_f32_e32 v1, 0x3e38aa3b, v1
	v_add_f32_e32 v0, v51, v0
	v_exp_f32_e32 v50, v1
	v_sub_f32_e32 v1, v52, v48
	v_add_f32_e32 v0, v54, v0
	v_mul_f32_e32 v1, 0x3e38aa3b, v1
	v_add_f32_e32 v0, v55, v0
	v_exp_f32_e32 v52, v1
	v_sub_f32_e32 v1, v123, v48
	v_add_f32_e32 v0, v57, v0
	v_mul_f32_e32 v1, 0x3e38aa3b, v1
	v_add_f32_e32 v0, v61, v0
	v_exp_f32_e32 v34, v1
	v_sub_f32_e32 v1, v122, v48
	v_add_f32_e32 v0, v64, v0
	v_mul_f32_e32 v1, 0x3e38aa3b, v1
	v_add_f32_e32 v0, v67, v0
	v_exp_f32_e32 v35, v1
	v_sub_f32_e32 v1, v121, v48
	v_add_f32_e32 v0, v42, v0
	v_mul_f32_e32 v1, 0x3e38aa3b, v1
	v_add_f32_e32 v0, v43, v0
	v_exp_f32_e32 v36, v1
	v_sub_f32_e32 v1, v120, v48
	v_add_f32_e32 v0, v45, v0
	v_mul_f32_e32 v1, 0x3e38aa3b, v1
	v_add_f32_e32 v0, v46, v0
	v_exp_f32_e32 v37, v1
	v_sub_f32_e32 v1, v119, v48
	v_add_f32_e32 v0, v47, v0
	v_mul_f32_e32 v1, 0x3e38aa3b, v1
	v_add_f32_e32 v0, v49, v0
	v_exp_f32_e32 v38, v1
	v_sub_f32_e32 v1, v118, v48
	v_add_f32_e32 v0, v50, v0
	v_mul_f32_e32 v1, 0x3e38aa3b, v1
	v_add_f32_e32 v0, v52, v0
	v_exp_f32_e32 v39, v1
	v_sub_f32_e32 v1, v117, v48
	v_add_f32_e32 v0, v34, v0
	v_mul_f32_e32 v1, 0x3e38aa3b, v1
	v_add_f32_e32 v0, v35, v0
	v_exp_f32_e32 v40, v1
	v_sub_f32_e32 v1, v116, v48
	v_add_f32_e32 v0, v36, v0
	v_mul_f32_e32 v1, 0x3e38aa3b, v1
	v_add_f32_e32 v0, v37, v0
	v_exp_f32_e32 v41, v1
	ds_read_b64_tr_b16 v[4:5], v177
	ds_read_b64_tr_b16 v[6:7], v177 offset:1536
	v_add_f32_e32 v0, v38, v0
	v_add_f32_e32 v0, v39, v0
	v_add_f32_e32 v0, v40, v0
	v_add_f32_e32 v32, v41, v0
	v_cvt_pk_bf16_f32 v0, v90, v92
	v_cvt_pk_bf16_f32 v1, v95, v98
	v_cvt_pk_bf16_f32 v2, v102, v108
	v_cvt_pk_bf16_f32 v3, v110, v112
	v_cvt_pk_bf16_f32 v118, v107, v113
	v_cvt_pk_bf16_f32 v119, v114, v115
	s_waitcnt lgkmcnt(0)
	v_mfma_f32_32x32x16_bf16 v[16:31], v[4:7], v[0:3], 0
	ds_read_b64_tr_b16 v[4:5], v177 offset:64
	ds_read_b64_tr_b16 v[6:7], v177 offset:1600
	ds_read_b64_tr_b16 v[112:113], v177 offset:3072
	ds_read_b64_tr_b16 v[114:115], v177 offset:4608
	v_cvt_pk_bf16_f32 v116, v91, v99
	v_cvt_pk_bf16_f32 v117, v103, v105
	v_cvt_pk_bf16_f32 v91, v93, v96
	v_cvt_pk_bf16_f32 v92, v100, v106
	v_cvt_pk_bf16_f32 v93, v109, v111
	s_waitcnt lgkmcnt(2)
	v_mfma_f32_32x32x16_bf16 v[0:15], v[4:7], v[0:3], 0
	v_cvt_pk_bf16_f32 v90, v82, v87
	v_cvt_pk_bf16_f32 v42, v42, v43
	v_cvt_pk_bf16_f32 v43, v45, v46
	v_cvt_pk_bf16_f32 v45, v50, v52
	v_cvt_pk_bf16_f32 v34, v34, v35
	v_cvt_pk_bf16_f32 v35, v36, v37
	v_cvt_pk_bf16_f32 v36, v38, v39
	s_waitcnt lgkmcnt(0)
	v_mfma_f32_32x32x16_bf16 v[16:31], v[112:115], v[116:119], v[16:31]
	ds_read_b64_tr_b16 v[112:113], v177 offset:3136
	ds_read_b64_tr_b16 v[114:115], v177 offset:4672
	ds_read_b64_tr_b16 v[106:107], v177 offset:6144
	ds_read_b64_tr_b16 v[108:109], v177 offset:7680
	v_cvt_pk_bf16_f32 v37, v40, v41
	v_mov_b32_e32 v33, v32
	s_nop 1
	v_permlane32_swap_b32_e32 v32, v33
	v_add_f32_e32 v32, v32, v33
	s_waitcnt lgkmcnt(2)
	v_mfma_f32_32x32x16_bf16 v[0:15], v[112:115], v[116:119], v[0:15]
	s_waitcnt lgkmcnt(0)
	v_mfma_f32_32x32x16_bf16 v[16:31], v[106:109], v[90:93], v[16:31]
	ds_read_b64_tr_b16 v[106:107], v177 offset:6208
	ds_read_b64_tr_b16 v[108:109], v177 offset:7744
	s_waitcnt lgkmcnt(0)
	v_mfma_f32_32x32x16_bf16 v[0:15], v[106:109], v[90:93], v[0:15]
	v_cvt_pk_bf16_f32 v92, v88, v97
	ds_read_b64_tr_b16 v[96:97], v177 offset:9216
	ds_read_b64_tr_b16 v[98:99], v177 offset:10752
	v_cvt_pk_bf16_f32 v90, v73, v78
	v_cvt_pk_bf16_f32 v91, v83, v85
	v_cvt_pk_bf16_f32 v93, v101, v104
	s_waitcnt lgkmcnt(0)
	s_nop 0
	v_mfma_f32_32x32x16_bf16 v[16:31], v[96:99], v[90:93], v[16:31]
	ds_read_b64_tr_b16 v[96:97], v177 offset:9280
	ds_read_b64_tr_b16 v[98:99], v177 offset:10816
	s_waitcnt lgkmcnt(0)
	v_mfma_f32_32x32x16_bf16 v[0:15], v[96:99], v[90:93], v[0:15]
	v_cvt_pk_bf16_f32 v92, v79, v86
	v_cvt_pk_bf16_f32 v93, v89, v94
	ds_read_b64_tr_b16 v[86:87], v177 offset:12288
	ds_read_b64_tr_b16 v[88:89], v177 offset:13824
	v_cvt_pk_bf16_f32 v90, v65, v70
	v_cvt_pk_bf16_f32 v91, v74, v76
	s_waitcnt lgkmcnt(0)
; __device__ __forceinline__ void attn_v2(const KA& A, const Ctx& F, int l) {
;     ...
;         else { if (F.tid == 0) *slot = 256u + __hip_atomic_fetch_add(ctr, 1u, __ATOMIC_RELAXED, __HIP_MEMORY_SCOPE_AGENT);
;                __syncthreads();
;                item = (int)*slot; }
;     ...
;         f32x16 o[2]; o[0] = f32x16{}; o[1] = f32x16{};
;         const unsigned char* vb = VI + ((32 * w + 4 * hh + ((lane & 15) >> 2)) * ATT_VS + 16 * ((lane >> 4) & 1) + 4 * (lane & 3)) * 2;
; #pragma unroll
;         for (int kt = 0; kt < 5; ++kt)
; #pragma unroll
;             for (int s = 0; s < 2; ++s) {
;                 v4u pw; pw.x = cvtpk(p[kt][8 * s + 0], p[kt][8 * s + 1]); pw.y = cvtpk(p[kt][8 * s + 2], p[kt][8 * s + 3]); pw.z = cvtpk(p[kt][8 * s + 4], p[kt][8 * s + 5]); pw.w = cvtpk(p[kt][8 * s + 6], p[kt][8 * s + 7]);
;                 const bf16x8_t pb = __builtin_bit_cast(bf16x8_t, pw);
; #pragma unroll
;                 for (int dt = 0; dt < 2; ++dt) {
;                     const unsigned char* vp = vb + ((32 * kt + 16 * s) * ATT_VS + 32 * dt) * 2;
;                     const v4i16_t lo = ds_tr16(vp), hi = ds_tr16(vp + 8 * ATT_VS * 2);
;                     const bf16x8_t va = (bf16x8_t){lo[0], lo[1], lo[2], lo[3], hi[0], hi[1], hi[2], hi[3]};
;                     o[dt] = __builtin_amdgcn_mfma_f32_32x32x16_bf16(va, pb, o[dt], 0, 0, 0);
;                 }
;             }
;         const float il = __builtin_amdgcn_rcpf(l);
;         bf16* op = PS + (tb + (size_t)(i0 + 32 * w + q) * dil) * PSW + C_Q + h * 64 + 8 * hh;
; #pragma unroll
;         for (int dt = 0; dt < 2; ++dt)
; #pragma unroll
;             for (int k2 = 0; k2 < 2; ++k2) { v2u wa, wb; const int ga = 8 * k2, gb = 8 * k2 + 4;
;                 wa.x = cvtpk(o[dt][ga + 0] * il, o[dt][ga + 1] * il); wa.y = cvtpk(o[dt][ga + 2] * il, o[dt][ga + 3] * il);
;                 wb.x = cvtpk(o[dt][gb + 0] * il, o[dt][gb + 1] * il); wb.y = cvtpk(o[dt][gb + 2] * il, o[dt][gb + 3] * il);
;                 const v4u wv = widen32(wa, wb);
;                 if (!(F.dry && (DRY_SEL & 2))) *(v4u*)(op + 32 * dt + 16 * k2) = wv; }
;         if (hh == 0 && !(F.dry && (DRY_SEL & 2))) LSE[(tb + (size_t)(i0 + 32 * w + q) * dil) * 6 + h] = mx * 0.125f + __builtin_amdgcn_logf(l) * 0.6931471805599453f;
;         asm volatile("s_waitcnt lgkmcnt(0)" ::: "memory"); __builtin_amdgcn_s_barrier(); asm volatile("" ::: "memory");
	s_nop 0
	v_mfma_f32_32x32x16_bf16 v[16:31], v[86:89], v[90:93], v[16:31]
	ds_read_b64_tr_b16 v[86:87], v177 offset:12352
	ds_read_b64_tr_b16 v[88:89], v177 offset:13888
	s_waitcnt lgkmcnt(0)
	v_mfma_f32_32x32x16_bf16 v[0:15], v[86:89], v[90:93], v[0:15]
	v_cvt_pk_bf16_f32 v88, v71, v77
	ds_read_b64_tr_b16 v[76:77], v177 offset:15360
	ds_read_b64_tr_b16 v[78:79], v177 offset:16896
	v_cvt_pk_bf16_f32 v86, v58, v62
	v_cvt_pk_bf16_f32 v87, v66, v68
	v_cvt_pk_bf16_f32 v89, v80, v84
	v_cvt_pk_bf16_f32 v58, v44, v51
	v_cvt_pk_bf16_f32 v44, v47, v49
	s_waitcnt lgkmcnt(0)
	v_mfma_f32_32x32x16_bf16 v[16:31], v[76:79], v[86:89], v[16:31]
	ds_read_b64_tr_b16 v[76:77], v177 offset:15424
	ds_read_b64_tr_b16 v[78:79], v177 offset:16960
	s_waitcnt lgkmcnt(0)
	v_mfma_f32_32x32x16_bf16 v[0:15], v[76:79], v[86:89], v[0:15]
	v_cvt_pk_bf16_f32 v78, v63, v69
	ds_read_b64_tr_b16 v[68:69], v177 offset:18432
	ds_read_b64_tr_b16 v[70:71], v177 offset:19968
	v_cvt_pk_bf16_f32 v76, v53, v56
	v_cvt_pk_bf16_f32 v77, v59, v60
	v_cvt_pk_bf16_f32 v79, v72, v75
	v_cvt_pk_bf16_f32 v59, v54, v55
	v_cvt_pk_bf16_f32 v60, v57, v61
	s_waitcnt lgkmcnt(0)
	v_mfma_f32_32x32x16_bf16 v[16:31], v[68:71], v[76:79], v[16:31]
	ds_read_b64_tr_b16 v[68:69], v177 offset:18496
	ds_read_b64_tr_b16 v[70:71], v177 offset:20032
	ds_read_b64_tr_b16 v[54:55], v177 offset:21504
	ds_read_b64_tr_b16 v[56:57], v177 offset:23040
	v_cvt_pk_bf16_f32 v61, v64, v67
	s_waitcnt lgkmcnt(2)
	v_mfma_f32_32x32x16_bf16 v[0:15], v[68:71], v[76:79], v[0:15]
	s_waitcnt lgkmcnt(0)
	v_mfma_f32_32x32x16_bf16 v[16:31], v[54:57], v[58:61], v[16:31]
	ds_read_b64_tr_b16 v[54:55], v177 offset:21568
	ds_read_b64_tr_b16 v[56:57], v177 offset:23104
	ds_read_b64_tr_b16 v[50:51], v177 offset:24576
	ds_read_b64_tr_b16 v[52:53], v177 offset:26112
	s_waitcnt lgkmcnt(2)
	v_mfma_f32_32x32x16_bf16 v[0:15], v[54:57], v[58:61], v[0:15]
	s_waitcnt lgkmcnt(0)
	v_mfma_f32_32x32x16_bf16 v[16:31], v[50:53], v[42:45], v[16:31]
	ds_read_b64_tr_b16 v[50:51], v177 offset:24640
	ds_read_b64_tr_b16 v[52:53], v177 offset:26176
	ds_read_b64_tr_b16 v[38:39], v177 offset:27648
	ds_read_b64_tr_b16 v[40:41], v177 offset:29184
	s_waitcnt lgkmcnt(2)
	v_mfma_f32_32x32x16_bf16 v[0:15], v[50:53], v[42:45], v[0:15]
	s_waitcnt lgkmcnt(0)
	v_mfma_f32_32x32x16_bf16 v[16:31], v[38:41], v[34:37], v[16:31]
	ds_read_b64_tr_b16 v[38:39], v177 offset:27712
	ds_read_b64_tr_b16 v[40:41], v177 offset:29248
	s_waitcnt lgkmcnt(0)
	v_mfma_f32_32x32x16_bf16 v[0:15], v[38:41], v[34:37], v[0:15]
	v_rcp_f32_e32 v34, v32
	s_nop 6
	v_pk_mul_f32 v[16:17], v[34:35], v[16:17] op_sel_hi:[0,1]
	v_pk_mul_f32 v[18:19], v[34:35], v[18:19] op_sel_hi:[0,1]
	v_cvt_pk_bf16_f32 v16, v16, v17
	s_nop 0
	v_pk_mul_f32 v[0:1], v[34:35], v[0:1] op_sel_hi:[0,1]
	v_pk_mul_f32 v[2:3], v[34:35], v[2:3] op_sel_hi:[0,1]
	v_cvt_pk_bf16_f32 v17, v18, v19
	v_pk_mul_f32 v[18:19], v[34:35], v[20:21] op_sel_hi:[0,1]
	v_pk_mul_f32 v[20:21], v[34:35], v[22:23] op_sel_hi:[0,1]
	v_cvt_pk_bf16_f32 v0, v0, v1
	v_cvt_pk_bf16_f32 v1, v2, v3
	v_pk_mul_f32 v[2:3], v[34:35], v[4:5] op_sel_hi:[0,1]
	v_pk_mul_f32 v[4:5], v[34:35], v[6:7] op_sel_hi:[0,1]
	v_cvt_pk_bf16_f32 v18, v18, v19
	v_cvt_pk_bf16_f32 v19, v20, v21
	v_cvt_pk_bf16_f32 v2, v2, v3
	v_cvt_pk_bf16_f32 v3, v4, v5
	v_permlane32_swap_b32_e32 v16, v18
	v_permlane32_swap_b32_e32 v17, v19
	v_permlane32_swap_b32_e32 v0, v2
	v_permlane32_swap_b32_e32 v1, v3
	global_store_dwordx4 v[140:141], v[16:19], off
	global_store_dwordx4 v[140:141], v[0:3], off offset:64
	v_pk_mul_f32 v[20:21], v[34:35], v[30:31] op_sel_hi:[0,1]
	v_pk_mul_f32 v[16:17], v[34:35], v[24:25] op_sel_hi:[0,1]
	v_pk_mul_f32 v[18:19], v[34:35], v[26:27] op_sel_hi:[0,1]
	v_pk_mul_f32 v[0:1], v[34:35], v[8:9] op_sel_hi:[0,1]
	v_pk_mul_f32 v[2:3], v[34:35], v[10:11] op_sel_hi:[0,1]
	v_cvt_pk_bf16_f32 v16, v16, v17
	v_cvt_pk_bf16_f32 v17, v18, v19
	v_pk_mul_f32 v[18:19], v[34:35], v[28:29] op_sel_hi:[0,1]
	v_cvt_pk_bf16_f32 v0, v0, v1
	v_cvt_pk_bf16_f32 v1, v2, v3
	v_pk_mul_f32 v[2:3], v[34:35], v[12:13] op_sel_hi:[0,1]
	v_pk_mul_f32 v[4:5], v[34:35], v[14:15] op_sel_hi:[0,1]
	v_cvt_pk_bf16_f32 v18, v18, v19
	v_cvt_pk_bf16_f32 v19, v20, v21
	v_cvt_pk_bf16_f32 v2, v2, v3
	v_cvt_pk_bf16_f32 v3, v4, v5
	v_permlane32_swap_b32_e32 v16, v18
	v_permlane32_swap_b32_e32 v17, v19
	v_permlane32_swap_b32_e32 v0, v2
	v_permlane32_swap_b32_e32 v1, v3
	global_store_dwordx4 v[140:141], v[16:19], off offset:32
	global_store_dwordx4 v[140:141], v[0:3], off offset:96
	s_and_saveexec_b64 s[10:11], s[38:39]
	s_cbranch_execz .LBB0_208
	v_log_f32_e32 v49, v32
	s_mov_b32 s12, 0x3e000000
	s_mov_b32 s13, 0x3f317218
	s_ashr_i32 s19, s18, 31
	v_pk_mul_f32 v[0:1], v[48:49], s[12:13]
	s_nop 0
	v_add_f32_e32 v4, v0, v1
	v_mad_u64_u32 v[0:1], s[12:13], v138, 24, s[0:1]
	v_mov_b32_e32 v2, v1
	v_mad_u64_u32 v[2:3], s[12:13], v139, 24, v[2:3]
	v_mov_b32_e32 v1, v2
	v_lshl_add_u64 v[0:1], s[18:19], 2, v[0:1]
	global_store_dword v[0:1], v4, off
.LBB0_208:
	s_or_b64 exec, exec, s[10:11]
	s_waitcnt lgkmcnt(0)
	s_barrier
	s_and_saveexec_b64 s[10:11], s[8:9]
	s_xor_b64 s[10:11], exec, s[10:11]
	s_cbranch_execz .LBB0_199
	s_mov_b64 s[14:15], exec
	v_mbcnt_lo_u32_b32 v0, s14, 0
	v_mbcnt_hi_u32_b32 v0, s15, v0
	v_cmp_eq_u32_e32 vcc, 0, v0
	s_and_saveexec_b64 s[12:13], vcc
	s_cbranch_execz .LBB0_198
	s_waitcnt vmcnt(5)
	v_mov_b32_e32 v1, v178
	s_branch .LBB0_198
